# diff loop: the four QK fragment reads of a 64-key step issued together (own registers), counted waits
# speedup vs baseline: 1.0084x; 1.0084x over previous
.LBB0_581:
	v_add_u32_e32 v161, s22, v218
	v_add_u32_e32 v160, s22, v217
	ds_read_b128 v[112:115], v161
	v_add_u32_e32 v222, s22, v216
	ds_read_b128 v[116:119], v160
	v_add_u32_e32 v221, s22, v215
	ds_read_b128 v[120:123], v222
	ds_read_b128 v[124:127], v221
	s_or_b32 s0, s23, s18
	s_cmp_eq_u32 s0, 0
	s_cselect_b64 s[14:15], -1, 0
	s_cmp_lg_u32 s0, 0
	s_cselect_b64 s[0:1], -1, 0
	s_and_b64 vcc, exec, s[14:15]
	s_mov_b64 s[2:3], s[14:15]
	s_waitcnt lgkmcnt(3)
	v_mfma_f32_32x32x16_bf16 v[96:111], v[112:115], v[152:155], v[64:79]
	s_waitcnt lgkmcnt(2)
	v_mfma_f32_32x32x16_bf16 v[96:111], v[116:119], v[144:147], v[96:111]
	s_waitcnt lgkmcnt(1)
	v_mfma_f32_32x32x16_bf16 v[128:143], v[120:123], v[148:151], v[80:95]
	s_waitcnt lgkmcnt(0)
	v_mfma_f32_32x32x16_bf16 v[128:143], v[124:127], v[156:159], v[128:143]
	s_nop 7
	v_max3_f32 v112, v96, v97, v98
	v_max_f32_e32 v112, v112, v99
	v_max3_f32 v112, v112, v100, v101
	v_max3_f32 v112, v112, v102, v103
	v_max3_f32 v112, v112, v104, v105
	v_max3_f32 v112, v112, v106, v107
	v_max3_f32 v112, v112, v108, v109
	v_max3_f32 v112, v112, v110, v111
	s_cbranch_vccnz .LBB0_583
	v_cmp_ge_f32_e32 vcc, s85, v112
	s_cmp_lg_u64 vcc, exec
	s_cselect_b64 s[2:3], -1, 0
